# down-proj residual epilogue regenerated: second half x loads issued before first half stores (reads overlap writes), one counted wait
# speedup vs baseline: 1.0133x; 1.0040x over previous
.LBB0_1077:
	v_lshl_or_b32 v150, s24, 8, v164
	v_lshl_add_u32 v160, s25, 8, v162
	v_ashrrev_i32_e32 v151, 31, v150
	v_lshlrev_b64 v[150:151], 2, v[150:151]
	v_ashrrev_i32_e32 v161, 31, v160
	v_lshl_add_u64 v[152:153], v[2:3], 0, v[150:151]
	v_lshlrev_b64 v[154:155], 12, v[160:161]
	v_lshl_add_u64 v[232:233], v[152:153], 0, v[154:155]
	s_mov_b64 s[14:15], 0x10000
	v_lshl_add_u64 v[234:235], v[232:233], 0, s[14:15]
	v_lshl_add_u64 v[236:237], v[234:235], 0, s[14:15]
	v_lshl_add_u64 v[238:239], v[236:237], 0, s[14:15]
	global_load_dwordx4 v[166:169], v[232:233], off
	global_load_dwordx4 v[170:173], v[232:233], off offset:16
	global_load_dwordx4 v[174:177], v[232:233], off offset:512
	global_load_dwordx4 v[178:181], v[232:233], off offset:528
	global_load_dwordx4 v[182:185], v[234:235], off
	global_load_dwordx4 v[186:189], v[234:235], off offset:16
	global_load_dwordx4 v[190:193], v[234:235], off offset:512
	global_load_dwordx4 v[194:197], v[234:235], off offset:528
	global_load_dwordx4 v[200:203], v[236:237], off
	global_load_dwordx4 v[204:207], v[236:237], off offset:16
	global_load_dwordx4 v[208:211], v[236:237], off offset:512
	global_load_dwordx4 v[212:215], v[236:237], off offset:528
	global_load_dwordx4 v[216:219], v[238:239], off
	global_load_dwordx4 v[220:223], v[238:239], off offset:16
	global_load_dwordx4 v[224:227], v[238:239], off offset:512
	global_load_dwordx4 v[228:231], v[238:239], off offset:528
	s_waitcnt vmcnt(0) lgkmcnt(0)
	v_pk_add_f32 v[128:129], v[128:129], v[166:167]
	v_pk_add_f32 v[130:131], v[130:131], v[168:169]
	v_pk_add_f32 v[124:125], v[124:125], v[170:171]
	v_pk_add_f32 v[126:127], v[126:127], v[172:173]
	v_pk_add_f32 v[112:113], v[112:113], v[174:175]
	v_pk_add_f32 v[114:115], v[114:115], v[176:177]
	v_pk_add_f32 v[104:105], v[104:105], v[178:179]
	v_pk_add_f32 v[106:107], v[106:107], v[180:181]
	v_pk_add_f32 v[120:121], v[120:121], v[182:183]
	v_pk_add_f32 v[122:123], v[122:123], v[184:185]
	v_pk_add_f32 v[116:117], v[116:117], v[186:187]
	v_pk_add_f32 v[118:119], v[118:119], v[188:189]
	v_pk_add_f32 v[96:97], v[96:97], v[190:191]
	v_pk_add_f32 v[98:99], v[98:99], v[192:193]
	v_pk_add_f32 v[88:89], v[88:89], v[194:195]
	v_pk_add_f32 v[90:91], v[90:91], v[196:197]
	v_pk_add_f32 v[108:109], v[108:109], v[200:201]
	v_pk_add_f32 v[110:111], v[110:111], v[202:203]
	v_pk_add_f32 v[100:101], v[100:101], v[204:205]
	v_pk_add_f32 v[102:103], v[102:103], v[206:207]
	v_pk_add_f32 v[80:81], v[80:81], v[208:209]
	v_pk_add_f32 v[82:83], v[82:83], v[210:211]
	v_pk_add_f32 v[76:77], v[76:77], v[212:213]
	v_pk_add_f32 v[78:79], v[78:79], v[214:215]
	v_pk_add_f32 v[92:93], v[92:93], v[216:217]
	v_pk_add_f32 v[94:95], v[94:95], v[218:219]
	v_pk_add_f32 v[84:85], v[84:85], v[220:221]
	v_pk_add_f32 v[86:87], v[86:87], v[222:223]
	v_pk_add_f32 v[72:73], v[72:73], v[224:225]
	v_pk_add_f32 v[74:75], v[74:75], v[226:227]
	v_pk_add_f32 v[68:69], v[68:69], v[228:229]
	v_pk_add_f32 v[70:71], v[70:71], v[230:231]
	s_mov_b64 s[14:15], 0x80000
	v_lshl_add_u64 v[150:151], v[232:233], 0, s[14:15]
	v_lshl_add_u64 v[152:153], v[234:235], 0, s[14:15]
	v_lshl_add_u64 v[154:155], v[236:237], 0, s[14:15]
	v_lshl_add_u64 v[156:157], v[238:239], 0, s[14:15]
	global_load_dwordx4 v[166:169], v[150:151], off
	global_load_dwordx4 v[170:173], v[150:151], off offset:16
	global_load_dwordx4 v[174:177], v[150:151], off offset:512
	global_load_dwordx4 v[178:181], v[150:151], off offset:528
	global_load_dwordx4 v[182:185], v[152:153], off
	global_load_dwordx4 v[186:189], v[152:153], off offset:16
	global_load_dwordx4 v[190:193], v[152:153], off offset:512
	global_load_dwordx4 v[194:197], v[152:153], off offset:528
	global_load_dwordx4 v[200:203], v[154:155], off
	global_load_dwordx4 v[204:207], v[154:155], off offset:16
	global_load_dwordx4 v[208:211], v[154:155], off offset:512
	global_load_dwordx4 v[212:215], v[154:155], off offset:528
	global_load_dwordx4 v[216:219], v[156:157], off
	global_load_dwordx4 v[220:223], v[156:157], off offset:16
	global_load_dwordx4 v[224:227], v[156:157], off offset:512
	global_load_dwordx4 v[228:231], v[156:157], off offset:528
	global_store_dwordx4 v[232:233], v[128:131], off
	global_store_dwordx4 v[232:233], v[124:127], off offset:16
	global_store_dwordx4 v[232:233], v[112:115], off offset:512
	global_store_dwordx4 v[232:233], v[104:107], off offset:528
	global_store_dwordx4 v[234:235], v[120:123], off
	global_store_dwordx4 v[234:235], v[116:119], off offset:16
	global_store_dwordx4 v[234:235], v[96:99], off offset:512
	global_store_dwordx4 v[234:235], v[88:91], off offset:528
	global_store_dwordx4 v[236:237], v[108:111], off
	global_store_dwordx4 v[236:237], v[100:103], off offset:16
	global_store_dwordx4 v[236:237], v[80:83], off offset:512
	global_store_dwordx4 v[236:237], v[76:79], off offset:528
	global_store_dwordx4 v[238:239], v[92:95], off
	global_store_dwordx4 v[238:239], v[84:87], off offset:16
	global_store_dwordx4 v[238:239], v[72:75], off offset:512
	global_store_dwordx4 v[238:239], v[68:71], off offset:528
	s_waitcnt vmcnt(16)
	v_pk_add_f32 v[64:65], v[64:65], v[166:167]
	v_pk_add_f32 v[66:67], v[66:67], v[168:169]
	v_pk_add_f32 v[60:61], v[60:61], v[170:171]
	v_pk_add_f32 v[62:63], v[62:63], v[172:173]
	v_pk_add_f32 v[52:53], v[52:53], v[174:175]
	v_pk_add_f32 v[54:55], v[54:55], v[176:177]
	v_pk_add_f32 v[44:45], v[44:45], v[178:179]
	v_pk_add_f32 v[46:47], v[46:47], v[180:181]
	v_pk_add_f32 v[56:57], v[56:57], v[182:183]
	v_pk_add_f32 v[58:59], v[58:59], v[184:185]
	v_pk_add_f32 v[48:49], v[48:49], v[186:187]
	v_pk_add_f32 v[50:51], v[50:51], v[188:189]
	v_pk_add_f32 v[36:37], v[36:37], v[190:191]
	v_pk_add_f32 v[38:39], v[38:39], v[192:193]
	v_pk_add_f32 v[28:29], v[28:29], v[194:195]
	v_pk_add_f32 v[30:31], v[30:31], v[196:197]
	v_pk_add_f32 v[40:41], v[40:41], v[200:201]
	v_pk_add_f32 v[42:43], v[42:43], v[202:203]
	v_pk_add_f32 v[32:33], v[32:33], v[204:205]
	v_pk_add_f32 v[34:35], v[34:35], v[206:207]
	v_pk_add_f32 v[20:21], v[20:21], v[208:209]
	v_pk_add_f32 v[22:23], v[22:23], v[210:211]
	v_pk_add_f32 v[12:13], v[12:13], v[212:213]
	v_pk_add_f32 v[14:15], v[14:15], v[214:215]
	v_pk_add_f32 v[24:25], v[24:25], v[216:217]
	v_pk_add_f32 v[26:27], v[26:27], v[218:219]
	v_pk_add_f32 v[16:17], v[16:17], v[220:221]
	v_pk_add_f32 v[18:19], v[18:19], v[222:223]
	v_pk_add_f32 v[8:9], v[8:9], v[224:225]
	v_pk_add_f32 v[10:11], v[10:11], v[226:227]
	v_pk_add_f32 v[4:5], v[4:5], v[228:229]
	v_pk_add_f32 v[6:7], v[6:7], v[230:231]
	global_store_dwordx4 v[150:151], v[64:67], off
	global_store_dwordx4 v[150:151], v[60:63], off offset:16
	global_store_dwordx4 v[150:151], v[52:55], off offset:512
	global_store_dwordx4 v[150:151], v[44:47], off offset:528
	global_store_dwordx4 v[152:153], v[56:59], off
	global_store_dwordx4 v[152:153], v[48:51], off offset:16
	global_store_dwordx4 v[152:153], v[36:39], off offset:512
	global_store_dwordx4 v[152:153], v[28:31], off offset:528
	global_store_dwordx4 v[154:155], v[40:43], off
	global_store_dwordx4 v[154:155], v[32:35], off offset:16
	global_store_dwordx4 v[154:155], v[20:23], off offset:512
	global_store_dwordx4 v[154:155], v[12:15], off offset:528
	global_store_dwordx4 v[156:157], v[24:27], off
	global_store_dwordx4 v[156:157], v[16:19], off offset:16
	global_store_dwordx4 v[156:157], v[8:11], off offset:512
	global_store_dwordx4 v[156:157], v[4:7], off offset:528
	s_mov_b64 s[14:15], -1
	s_andn2_b64 vcc, exec, s[4:5]
	s_cbranch_vccnz .LBB0_1066
	s_andn2_b64 vcc, exec, s[6:7]
	s_cbranch_vccnz .LBB0_1065
	s_barrier
	s_branch .LBB0_1065
